# XCD-local seams invalidate the L1 while waiting and the last arriver releases its XCD at once
# speedup vs baseline: 1.0661x; 1.0055x over previous
.LBB0_413:
	s_or_b64 exec, exec, s[10:11]
	v_cvt_f32_u32_e32 v2, s80
	s_cmp_eq_u32 s101, 0
	s_cbranch_scc1 .Lxn1
	buffer_inv sc1
	s_waitcnt vmcnt(1)
	s_branch .Lxj1

.Lxj1:
	v_readfirstlane_b32 s8, v1
	s_sub_i32 s9, 0, s80
	v_rcp_iflag_f32_e32 v2, v2
	v_add_u32_e32 v1, s8, v0
	v_mul_f32_e32 v2, 0x4f7ffffe, v2
	v_cvt_u32_f32_e32 v2, v2
	v_mul_lo_u32 v0, s9, v2
	v_mul_hi_u32 v0, v2, v0
	v_add_u32_e32 v0, v2, v0
	v_mul_hi_u32 v0, v1, v0
	v_mul_lo_u32 v2, v0, s80
	v_sub_u32_e32 v2, v1, v2
	v_add_u32_e32 v3, 1, v0
	v_cmp_le_u32_e32 vcc, s80, v2
	v_add_u32_e32 v1, 1, v1
	s_nop 0
	v_cndmask_b32_e32 v0, v0, v3, vcc
	v_subrev_u32_e32 v3, s80, v2
	v_cndmask_b32_e32 v2, v2, v3, vcc
	v_add_u32_e32 v3, 1, v0
	v_cmp_le_u32_e32 vcc, s80, v2
	s_nop 1
	v_cndmask_b32_e32 v0, v0, v3, vcc
	v_mul_lo_u32 v2, s80, v0
	v_add_u32_e32 v2, s80, v2
	v_cmp_ne_u32_e32 vcc, v1, v2
	s_and_saveexec_b64 s[8:9], vcc
	s_xor_b64 s[8:9], exec, s[8:9]
	s_cbranch_execz .LBB0_427
	v_mov_b32_e32 v1, 0x2000
	global_load_dword v1, v1, s[6:7] offset:1024 sc1
	s_add_u32 s22, s6, 0x2400
	s_addc_u32 s23, s7, 0
	s_waitcnt vmcnt(0)
	v_cmp_eq_u32_e32 vcc, v1, v0
	s_and_saveexec_b64 s[10:11], vcc
	s_cbranch_execz .LBB0_426
	s_add_u32 s12, s60, 0x1400200
	s_addc_u32 s13, s61, 0
	s_mov_b32 s36, 1
	s_mov_b64 s[24:25], 0
	v_mov_b32_e32 v1, 0
	s_branch .LBB0_417

.LBB0_426:
	s_or_b64 exec, exec, s[10:11]
	s_waitcnt vmcnt(0)
	s_cmp_lg_u32 s101, 0
	s_cbranch_scc1 .Lxs1
	buffer_inv sc1

.LBB0_427:
	s_andn2_saveexec_b64 s[8:9], s[8:9]
	s_cbranch_execz .LBB0_447
	s_mov_b64 s[8:9], exec
	s_cmp_eq_u32 s101, 0
	s_cbranch_scc1 .Lxf1
	v_mov_b32_e32 v0, 0x2000
	v_mov_b32_e32 v1, 1
	global_atomic_add v0, v1, s[6:7] offset:1024
	s_waitcnt vmcnt(0)
	s_branch .LBB0_447
.Lxf1:
	buffer_wbl2 sc1
	s_waitcnt vmcnt(0)
	v_mbcnt_lo_u32_b32 v0, s8, 0
	v_mbcnt_hi_u32_b32 v0, s9, v0
	v_cmp_eq_u32_e32 vcc, 0, v0
	s_and_saveexec_b64 s[10:11], vcc
	s_cbranch_execz .LBB0_430
	s_bcnt1_i32_b64 s8, s[8:9]
	v_mov_b32_e32 v1, 0x1403000
	v_mov_b32_e32 v2, s8
	global_atomic_add v1, v1, v2, s[60:61] offset:1024 sc0

.Lxj2:
	v_readfirstlane_b32 s8, v1
	s_sub_i32 s9, 0, s80
	v_rcp_iflag_f32_e32 v2, v2
	v_add_u32_e32 v1, s8, v0
	v_mul_f32_e32 v2, 0x4f7ffffe, v2
	v_cvt_u32_f32_e32 v2, v2
	v_mul_lo_u32 v0, s9, v2
	v_mul_hi_u32 v0, v2, v0
	v_add_u32_e32 v0, v2, v0
	v_mul_hi_u32 v0, v1, v0
	v_mul_lo_u32 v2, v0, s80
	v_sub_u32_e32 v2, v1, v2
	v_add_u32_e32 v3, 1, v0
	v_cmp_le_u32_e32 vcc, s80, v2
	v_add_u32_e32 v1, 1, v1
	s_nop 0
	v_cndmask_b32_e32 v0, v0, v3, vcc
	v_subrev_u32_e32 v3, s80, v2
	v_cndmask_b32_e32 v2, v2, v3, vcc
	v_add_u32_e32 v3, 1, v0
	v_cmp_le_u32_e32 vcc, s80, v2
	s_nop 1
	v_cndmask_b32_e32 v0, v0, v3, vcc
	v_mul_lo_u32 v2, s80, v0
	v_add_u32_e32 v2, s80, v2
	v_cmp_ne_u32_e32 vcc, v1, v2
	s_and_saveexec_b64 s[8:9], vcc
	s_xor_b64 s[8:9], exec, s[8:9]
	s_cbranch_execz .LBB0_486
	v_mov_b32_e32 v1, 0x2000
	global_load_dword v1, v1, s[6:7] offset:1024 sc1
	s_add_u32 s14, s6, 0x2400
	s_addc_u32 s15, s7, 0
	s_waitcnt vmcnt(0)
	v_cmp_eq_u32_e32 vcc, v1, v0
	s_and_saveexec_b64 s[10:11], vcc
	s_cbranch_execz .LBB0_485
	s_add_u32 s12, s60, 0x1400200
	s_addc_u32 s13, s61, 0
	s_mov_b32 s26, 1
	s_mov_b64 s[16:17], 0
	v_mov_b32_e32 v1, 0
	s_branch .LBB0_476

.LBB0_814:
	s_or_b64 exec, exec, s[8:9]
	v_cvt_f32_u32_e32 v2, s80
	s_cmp_eq_u32 s101, 0
	s_cbranch_scc1 .Lxn6
	buffer_inv sc1
	s_waitcnt vmcnt(1)
	s_branch .Lxj6

.Lxj6:
	v_readfirstlane_b32 s6, v1
	s_sub_i32 s7, 0, s80
	v_rcp_iflag_f32_e32 v2, v2
	v_add_u32_e32 v1, s6, v0
	v_mul_f32_e32 v2, 0x4f7ffffe, v2
	v_cvt_u32_f32_e32 v2, v2
	v_mul_lo_u32 v0, s7, v2
	v_mul_hi_u32 v0, v2, v0
	v_add_u32_e32 v0, v2, v0
	v_mul_hi_u32 v0, v1, v0
	v_mul_lo_u32 v2, v0, s80
	v_sub_u32_e32 v2, v1, v2
	v_add_u32_e32 v3, 1, v0
	v_cmp_le_u32_e32 vcc, s80, v2
	v_add_u32_e32 v1, 1, v1
	s_nop 0
	v_cndmask_b32_e32 v0, v0, v3, vcc
	v_subrev_u32_e32 v3, s80, v2
	v_cndmask_b32_e32 v2, v2, v3, vcc
	v_add_u32_e32 v3, 1, v0
	v_cmp_le_u32_e32 vcc, s80, v2
	s_nop 1
	v_cndmask_b32_e32 v0, v0, v3, vcc
	v_mul_lo_u32 v2, s80, v0
	v_add_u32_e32 v2, s80, v2
	v_cmp_ne_u32_e32 vcc, v1, v2
	s_and_saveexec_b64 s[6:7], vcc
	s_xor_b64 s[6:7], exec, s[6:7]
	s_cbranch_execz .LBB0_828
	v_mov_b32_e32 v1, 0x2000
	global_load_dword v1, v1, s[4:5] offset:1024 sc1
	s_add_u32 s12, s4, 0x2400
	s_addc_u32 s13, s5, 0
	s_waitcnt vmcnt(0)
	v_cmp_eq_u32_e32 vcc, v1, v0
	s_and_saveexec_b64 s[8:9], vcc
	s_cbranch_execz .LBB0_827
	s_add_u32 s10, s60, 0x1400200
	s_addc_u32 s11, s61, 0
	s_mov_b32 s24, 1
	s_mov_b64 s[14:15], 0
	v_mov_b32_e32 v1, 0
	s_branch .LBB0_818

.LBB0_827:
	s_or_b64 exec, exec, s[8:9]
	s_waitcnt vmcnt(0)
	s_cmp_lg_u32 s101, 0
	s_cbranch_scc1 .Lxs6
	buffer_inv sc1

.LBB0_828:
	s_andn2_saveexec_b64 s[6:7], s[6:7]
	s_cbranch_execz .LBB0_848
	s_mov_b64 s[6:7], exec
	s_cmp_eq_u32 s101, 0
	s_cbranch_scc1 .Lxf6
	v_mov_b32_e32 v0, 0x2000
	v_mov_b32_e32 v1, 1
	global_atomic_add v0, v1, s[4:5] offset:1024
	s_waitcnt vmcnt(0)
	s_branch .LBB0_848
.Lxf6:
	buffer_wbl2 sc1
	s_waitcnt vmcnt(0)
	v_mbcnt_lo_u32_b32 v0, s6, 0
	v_mbcnt_hi_u32_b32 v0, s7, v0
	v_cmp_eq_u32_e32 vcc, 0, v0
	s_and_saveexec_b64 s[8:9], vcc
	s_cbranch_execz .LBB0_831
	s_bcnt1_i32_b64 s6, s[6:7]
	v_mov_b32_e32 v1, 0x1403000
	v_mov_b32_e32 v2, s6
	global_atomic_add v1, v1, v2, s[60:61] offset:1024 sc0
